# P0: silu(c) staging loop unrolled (34 loads in flight instead of 34 serialized load-wait-compute-write iterations); on top of v32
# speedup vs baseline: 1.0037x; 1.0037x over previous
.LBB0_512:
	s_or_b64 exec, exec, s[0:1]
	v_cmp_gt_i32_e32 vcc, s10, v156
	s_and_saveexec_b64 s[0:1], vcc
	v_readlane_b32 s8, v250, 3
	v_readlane_b32 s10, v250, 5
	v_readlane_b32 s11, v250, 6
	v_readlane_b32 s14, v250, 9
	v_readlane_b32 s15, v250, 10
	s_movk_i32 s8, 0x4000
	v_readlane_b32 s9, v250, 4
	v_readlane_b32 s12, v250, 7
	v_readlane_b32 s13, v250, 8
	v_readlane_b32 s16, v250, 11
	v_readlane_b32 s17, v250, 12
	v_readlane_b32 s18, v250, 13
	v_readlane_b32 s19, v250, 14
	v_readlane_b32 s20, v250, 15
	v_readlane_b32 s21, v250, 16
	v_readlane_b32 s22, v250, 17
	v_readlane_b32 s23, v250, 18
	s_cbranch_execz .LBB0_515
	v_ashrrev_i32_e32 v157, 31, v156
	v_lshl_add_u32 v2, v156, 2, 0
	v_lshl_add_u64 v[0:1], v[156:157], 2, s[10:11]
	v_lshl_add_u64 v[4:5], v[156:157], 2, s[14:15]
	s_mov_b64 s[4:5], 0x1000
	global_load_dword v8, v[0:1], off
	global_load_dword v9, v[0:1], off offset:2048
	v_lshl_add_u64 v[0:1], v[0:1], 0, s[4:5]
	global_load_dword v10, v[0:1], off
	global_load_dword v11, v[0:1], off offset:2048
	v_lshl_add_u64 v[0:1], v[0:1], 0, s[4:5]
	global_load_dword v12, v[0:1], off
	global_load_dword v13, v[0:1], off offset:2048
	v_lshl_add_u64 v[0:1], v[0:1], 0, s[4:5]
	global_load_dword v14, v[0:1], off
	global_load_dword v15, v[0:1], off offset:2048
	v_lshl_add_u64 v[0:1], v[0:1], 0, s[4:5]
	global_load_dword v16, v[0:1], off
	global_load_dword v17, v[0:1], off offset:2048
	v_lshl_add_u64 v[0:1], v[0:1], 0, s[4:5]
	global_load_dword v18, v[0:1], off
	global_load_dword v19, v[0:1], off offset:2048
	v_lshl_add_u64 v[0:1], v[0:1], 0, s[4:5]
	global_load_dword v20, v[0:1], off
	global_load_dword v21, v[0:1], off offset:2048
	v_lshl_add_u64 v[0:1], v[0:1], 0, s[4:5]
	global_load_dword v22, v[0:1], off
	global_load_dword v23, v[0:1], off offset:2048
	v_lshl_add_u64 v[0:1], v[0:1], 0, s[4:5]
	global_load_dword v24, v[0:1], off
	global_load_dword v25, v[0:1], off offset:2048
	v_lshl_add_u64 v[0:1], v[0:1], 0, s[4:5]
	global_load_dword v26, v[0:1], off
	global_load_dword v27, v[0:1], off offset:2048
	v_lshl_add_u64 v[0:1], v[0:1], 0, s[4:5]
	global_load_dword v28, v[0:1], off
	global_load_dword v29, v[0:1], off offset:2048
	v_lshl_add_u64 v[0:1], v[0:1], 0, s[4:5]
	global_load_dword v30, v[0:1], off
	global_load_dword v31, v[0:1], off offset:2048
	v_lshl_add_u64 v[0:1], v[0:1], 0, s[4:5]
	global_load_dword v32, v[0:1], off
	global_load_dword v33, v[0:1], off offset:2048
	v_lshl_add_u64 v[0:1], v[0:1], 0, s[4:5]
	global_load_dword v34, v[0:1], off
	global_load_dword v35, v[0:1], off offset:2048
	v_lshl_add_u64 v[0:1], v[0:1], 0, s[4:5]
	global_load_dword v36, v[0:1], off
	global_load_dword v37, v[0:1], off offset:2048
	v_lshl_add_u64 v[0:1], v[0:1], 0, s[4:5]
	global_load_dword v38, v[0:1], off
	global_load_dword v39, v[0:1], off offset:2048
	global_load_dword v40, v[4:5], off
	global_load_dword v41, v[4:5], off offset:2048
	v_add_u32_e32 v6, 0x10000, v2
	s_waitcnt vmcnt(33)
	v_mul_f32_e32 v42, 0xbfb8aa3b, v8
	v_exp_f32_e32 v42, v42
	s_nop 0
	v_add_f32_e32 v42, 1.0, v42
	v_div_scale_f32 v43, s[4:5], v42, v42, v8
	v_rcp_f32_e32 v44, v43
	v_div_scale_f32 v45, vcc, v8, v42, v8
	v_fma_f32 v46, -v43, v44, 1.0
	v_fmac_f32_e32 v44, v46, v44
	v_mul_f32_e32 v46, v45, v44
	v_fma_f32 v47, -v43, v46, v45
	v_fmac_f32_e32 v46, v47, v44
	v_fma_f32 v43, -v43, v46, v45
	v_div_fmas_f32 v43, v43, v44, v46
	v_div_fixup_f32 v8, v43, v42, v8
	ds_write_b32 v2, v8
	s_waitcnt vmcnt(32)
	v_mul_f32_e32 v42, 0xbfb8aa3b, v9
	v_exp_f32_e32 v42, v42
	s_nop 0
	v_add_f32_e32 v42, 1.0, v42
	v_div_scale_f32 v43, s[4:5], v42, v42, v9
	v_rcp_f32_e32 v44, v43
	v_div_scale_f32 v45, vcc, v9, v42, v9
	v_fma_f32 v46, -v43, v44, 1.0
	v_fmac_f32_e32 v44, v46, v44
	v_mul_f32_e32 v46, v45, v44
	v_fma_f32 v47, -v43, v46, v45
	v_fmac_f32_e32 v46, v47, v44
	v_fma_f32 v43, -v43, v46, v45
	v_div_fmas_f32 v43, v43, v44, v46
	v_div_fixup_f32 v9, v43, v42, v9
	ds_write_b32 v2, v9 offset:2048
	s_waitcnt vmcnt(31)
	v_mul_f32_e32 v42, 0xbfb8aa3b, v10
	v_exp_f32_e32 v42, v42
	s_nop 0
	v_add_f32_e32 v42, 1.0, v42
	v_div_scale_f32 v43, s[4:5], v42, v42, v10
	v_rcp_f32_e32 v44, v43
	v_div_scale_f32 v45, vcc, v10, v42, v10
	v_fma_f32 v46, -v43, v44, 1.0
	v_fmac_f32_e32 v44, v46, v44
	v_mul_f32_e32 v46, v45, v44
	v_fma_f32 v47, -v43, v46, v45
	v_fmac_f32_e32 v46, v47, v44
	v_fma_f32 v43, -v43, v46, v45
	v_div_fmas_f32 v43, v43, v44, v46
	v_div_fixup_f32 v10, v43, v42, v10
	ds_write_b32 v2, v10 offset:4096
	s_waitcnt vmcnt(30)
	v_mul_f32_e32 v42, 0xbfb8aa3b, v11
	v_exp_f32_e32 v42, v42
	s_nop 0
	v_add_f32_e32 v42, 1.0, v42
	v_div_scale_f32 v43, s[4:5], v42, v42, v11
	v_rcp_f32_e32 v44, v43
	v_div_scale_f32 v45, vcc, v11, v42, v11
	v_fma_f32 v46, -v43, v44, 1.0
	v_fmac_f32_e32 v44, v46, v44
	v_mul_f32_e32 v46, v45, v44
	v_fma_f32 v47, -v43, v46, v45
	v_fmac_f32_e32 v46, v47, v44
	v_fma_f32 v43, -v43, v46, v45
	v_div_fmas_f32 v43, v43, v44, v46
	v_div_fixup_f32 v11, v43, v42, v11
	ds_write_b32 v2, v11 offset:6144
	s_waitcnt vmcnt(29)
	v_mul_f32_e32 v42, 0xbfb8aa3b, v12
	v_exp_f32_e32 v42, v42
	s_nop 0
	v_add_f32_e32 v42, 1.0, v42
	v_div_scale_f32 v43, s[4:5], v42, v42, v12
	v_rcp_f32_e32 v44, v43
	v_div_scale_f32 v45, vcc, v12, v42, v12
	v_fma_f32 v46, -v43, v44, 1.0
	v_fmac_f32_e32 v44, v46, v44
	v_mul_f32_e32 v46, v45, v44
	v_fma_f32 v47, -v43, v46, v45
	v_fmac_f32_e32 v46, v47, v44
	v_fma_f32 v43, -v43, v46, v45
	v_div_fmas_f32 v43, v43, v44, v46
	v_div_fixup_f32 v12, v43, v42, v12
	ds_write_b32 v2, v12 offset:8192
	s_waitcnt vmcnt(28)
	v_mul_f32_e32 v42, 0xbfb8aa3b, v13
	v_exp_f32_e32 v42, v42
	s_nop 0
	v_add_f32_e32 v42, 1.0, v42
	v_div_scale_f32 v43, s[4:5], v42, v42, v13
	v_rcp_f32_e32 v44, v43
	v_div_scale_f32 v45, vcc, v13, v42, v13
	v_fma_f32 v46, -v43, v44, 1.0
	v_fmac_f32_e32 v44, v46, v44
	v_mul_f32_e32 v46, v45, v44
	v_fma_f32 v47, -v43, v46, v45
	v_fmac_f32_e32 v46, v47, v44
	v_fma_f32 v43, -v43, v46, v45
	v_div_fmas_f32 v43, v43, v44, v46
	v_div_fixup_f32 v13, v43, v42, v13
	ds_write_b32 v2, v13 offset:10240
	s_waitcnt vmcnt(27)
	v_mul_f32_e32 v42, 0xbfb8aa3b, v14
	v_exp_f32_e32 v42, v42
	s_nop 0
	v_add_f32_e32 v42, 1.0, v42
	v_div_scale_f32 v43, s[4:5], v42, v42, v14
	v_rcp_f32_e32 v44, v43
	v_div_scale_f32 v45, vcc, v14, v42, v14
	v_fma_f32 v46, -v43, v44, 1.0
	v_fmac_f32_e32 v44, v46, v44
	v_mul_f32_e32 v46, v45, v44
	v_fma_f32 v47, -v43, v46, v45
	v_fmac_f32_e32 v46, v47, v44
	v_fma_f32 v43, -v43, v46, v45
	v_div_fmas_f32 v43, v43, v44, v46
	v_div_fixup_f32 v14, v43, v42, v14
	ds_write_b32 v2, v14 offset:12288
	s_waitcnt vmcnt(26)
	v_mul_f32_e32 v42, 0xbfb8aa3b, v15
	v_exp_f32_e32 v42, v42
	s_nop 0
	v_add_f32_e32 v42, 1.0, v42
	v_div_scale_f32 v43, s[4:5], v42, v42, v15
	v_rcp_f32_e32 v44, v43
	v_div_scale_f32 v45, vcc, v15, v42, v15
	v_fma_f32 v46, -v43, v44, 1.0
	v_fmac_f32_e32 v44, v46, v44
	v_mul_f32_e32 v46, v45, v44
	v_fma_f32 v47, -v43, v46, v45
	v_fmac_f32_e32 v46, v47, v44
	v_fma_f32 v43, -v43, v46, v45
	v_div_fmas_f32 v43, v43, v44, v46
	v_div_fixup_f32 v15, v43, v42, v15
	ds_write_b32 v2, v15 offset:14336
	s_waitcnt vmcnt(25)
	v_mul_f32_e32 v42, 0xbfb8aa3b, v16
	v_exp_f32_e32 v42, v42
	s_nop 0
	v_add_f32_e32 v42, 1.0, v42
	v_div_scale_f32 v43, s[4:5], v42, v42, v16
	v_rcp_f32_e32 v44, v43
	v_div_scale_f32 v45, vcc, v16, v42, v16
	v_fma_f32 v46, -v43, v44, 1.0
	v_fmac_f32_e32 v44, v46, v44
	v_mul_f32_e32 v46, v45, v44
	v_fma_f32 v47, -v43, v46, v45
	v_fmac_f32_e32 v46, v47, v44
	v_fma_f32 v43, -v43, v46, v45
	v_div_fmas_f32 v43, v43, v44, v46
	v_div_fixup_f32 v16, v43, v42, v16
	ds_write_b32 v2, v16 offset:16384
	s_waitcnt vmcnt(24)
	v_mul_f32_e32 v42, 0xbfb8aa3b, v17
	v_exp_f32_e32 v42, v42
	s_nop 0
	v_add_f32_e32 v42, 1.0, v42
	v_div_scale_f32 v43, s[4:5], v42, v42, v17
	v_rcp_f32_e32 v44, v43
	v_div_scale_f32 v45, vcc, v17, v42, v17
	v_fma_f32 v46, -v43, v44, 1.0
	v_fmac_f32_e32 v44, v46, v44
	v_mul_f32_e32 v46, v45, v44
	v_fma_f32 v47, -v43, v46, v45
	v_fmac_f32_e32 v46, v47, v44
	v_fma_f32 v43, -v43, v46, v45
	v_div_fmas_f32 v43, v43, v44, v46
	v_div_fixup_f32 v17, v43, v42, v17
	ds_write_b32 v2, v17 offset:18432
	s_waitcnt vmcnt(23)
	v_mul_f32_e32 v42, 0xbfb8aa3b, v18
	v_exp_f32_e32 v42, v42
	s_nop 0
	v_add_f32_e32 v42, 1.0, v42
	v_div_scale_f32 v43, s[4:5], v42, v42, v18
	v_rcp_f32_e32 v44, v43
	v_div_scale_f32 v45, vcc, v18, v42, v18
	v_fma_f32 v46, -v43, v44, 1.0
	v_fmac_f32_e32 v44, v46, v44
	v_mul_f32_e32 v46, v45, v44
	v_fma_f32 v47, -v43, v46, v45
	v_fmac_f32_e32 v46, v47, v44
	v_fma_f32 v43, -v43, v46, v45
	v_div_fmas_f32 v43, v43, v44, v46
	v_div_fixup_f32 v18, v43, v42, v18
	ds_write_b32 v2, v18 offset:20480
	s_waitcnt vmcnt(22)
	v_mul_f32_e32 v42, 0xbfb8aa3b, v19
	v_exp_f32_e32 v42, v42
	s_nop 0
	v_add_f32_e32 v42, 1.0, v42
	v_div_scale_f32 v43, s[4:5], v42, v42, v19
	v_rcp_f32_e32 v44, v43
	v_div_scale_f32 v45, vcc, v19, v42, v19
	v_fma_f32 v46, -v43, v44, 1.0
	v_fmac_f32_e32 v44, v46, v44
	v_mul_f32_e32 v46, v45, v44
	v_fma_f32 v47, -v43, v46, v45
	v_fmac_f32_e32 v46, v47, v44
	v_fma_f32 v43, -v43, v46, v45
	v_div_fmas_f32 v43, v43, v44, v46
	v_div_fixup_f32 v19, v43, v42, v19
	ds_write_b32 v2, v19 offset:22528
	s_waitcnt vmcnt(21)
	v_mul_f32_e32 v42, 0xbfb8aa3b, v20
	v_exp_f32_e32 v42, v42
	s_nop 0
	v_add_f32_e32 v42, 1.0, v42
	v_div_scale_f32 v43, s[4:5], v42, v42, v20
	v_rcp_f32_e32 v44, v43
	v_div_scale_f32 v45, vcc, v20, v42, v20
	v_fma_f32 v46, -v43, v44, 1.0
	v_fmac_f32_e32 v44, v46, v44
	v_mul_f32_e32 v46, v45, v44
	v_fma_f32 v47, -v43, v46, v45
	v_fmac_f32_e32 v46, v47, v44
	v_fma_f32 v43, -v43, v46, v45
	v_div_fmas_f32 v43, v43, v44, v46
	v_div_fixup_f32 v20, v43, v42, v20
	ds_write_b32 v2, v20 offset:24576
	s_waitcnt vmcnt(20)
	v_mul_f32_e32 v42, 0xbfb8aa3b, v21
	v_exp_f32_e32 v42, v42
	s_nop 0
	v_add_f32_e32 v42, 1.0, v42
	v_div_scale_f32 v43, s[4:5], v42, v42, v21
	v_rcp_f32_e32 v44, v43
	v_div_scale_f32 v45, vcc, v21, v42, v21
	v_fma_f32 v46, -v43, v44, 1.0
	v_fmac_f32_e32 v44, v46, v44
	v_mul_f32_e32 v46, v45, v44
	v_fma_f32 v47, -v43, v46, v45
	v_fmac_f32_e32 v46, v47, v44
	v_fma_f32 v43, -v43, v46, v45
	v_div_fmas_f32 v43, v43, v44, v46
	v_div_fixup_f32 v21, v43, v42, v21
	ds_write_b32 v2, v21 offset:26624
	s_waitcnt vmcnt(19)
	v_mul_f32_e32 v42, 0xbfb8aa3b, v22
	v_exp_f32_e32 v42, v42
	s_nop 0
	v_add_f32_e32 v42, 1.0, v42
	v_div_scale_f32 v43, s[4:5], v42, v42, v22
	v_rcp_f32_e32 v44, v43
	v_div_scale_f32 v45, vcc, v22, v42, v22
	v_fma_f32 v46, -v43, v44, 1.0
	v_fmac_f32_e32 v44, v46, v44
	v_mul_f32_e32 v46, v45, v44
	v_fma_f32 v47, -v43, v46, v45
	v_fmac_f32_e32 v46, v47, v44
	v_fma_f32 v43, -v43, v46, v45
	v_div_fmas_f32 v43, v43, v44, v46
	v_div_fixup_f32 v22, v43, v42, v22
	ds_write_b32 v2, v22 offset:28672
	s_waitcnt vmcnt(18)
	v_mul_f32_e32 v42, 0xbfb8aa3b, v23
	v_exp_f32_e32 v42, v42
	s_nop 0
	v_add_f32_e32 v42, 1.0, v42
	v_div_scale_f32 v43, s[4:5], v42, v42, v23
	v_rcp_f32_e32 v44, v43
	v_div_scale_f32 v45, vcc, v23, v42, v23
	v_fma_f32 v46, -v43, v44, 1.0
	v_fmac_f32_e32 v44, v46, v44
	v_mul_f32_e32 v46, v45, v44
	v_fma_f32 v47, -v43, v46, v45
	v_fmac_f32_e32 v46, v47, v44
	v_fma_f32 v43, -v43, v46, v45
	v_div_fmas_f32 v43, v43, v44, v46
	v_div_fixup_f32 v23, v43, v42, v23
	ds_write_b32 v2, v23 offset:30720
	s_waitcnt vmcnt(17)
	v_mul_f32_e32 v42, 0xbfb8aa3b, v24
	v_exp_f32_e32 v42, v42
	s_nop 0
	v_add_f32_e32 v42, 1.0, v42
	v_div_scale_f32 v43, s[4:5], v42, v42, v24
	v_rcp_f32_e32 v44, v43
	v_div_scale_f32 v45, vcc, v24, v42, v24
	v_fma_f32 v46, -v43, v44, 1.0
	v_fmac_f32_e32 v44, v46, v44
	v_mul_f32_e32 v46, v45, v44
	v_fma_f32 v47, -v43, v46, v45
	v_fmac_f32_e32 v46, v47, v44
	v_fma_f32 v43, -v43, v46, v45
	v_div_fmas_f32 v43, v43, v44, v46
	v_div_fixup_f32 v24, v43, v42, v24
	ds_write_b32 v2, v24 offset:32768
	s_waitcnt vmcnt(16)
	v_mul_f32_e32 v42, 0xbfb8aa3b, v25
	v_exp_f32_e32 v42, v42
	s_nop 0
	v_add_f32_e32 v42, 1.0, v42
	v_div_scale_f32 v43, s[4:5], v42, v42, v25
	v_rcp_f32_e32 v44, v43
	v_div_scale_f32 v45, vcc, v25, v42, v25
	v_fma_f32 v46, -v43, v44, 1.0
	v_fmac_f32_e32 v44, v46, v44
	v_mul_f32_e32 v46, v45, v44
	v_fma_f32 v47, -v43, v46, v45
	v_fmac_f32_e32 v46, v47, v44
	v_fma_f32 v43, -v43, v46, v45
	v_div_fmas_f32 v43, v43, v44, v46
	v_div_fixup_f32 v25, v43, v42, v25
	ds_write_b32 v2, v25 offset:34816
	s_waitcnt vmcnt(15)
	v_mul_f32_e32 v42, 0xbfb8aa3b, v26
	v_exp_f32_e32 v42, v42
	s_nop 0
	v_add_f32_e32 v42, 1.0, v42
	v_div_scale_f32 v43, s[4:5], v42, v42, v26
	v_rcp_f32_e32 v44, v43
	v_div_scale_f32 v45, vcc, v26, v42, v26
	v_fma_f32 v46, -v43, v44, 1.0
	v_fmac_f32_e32 v44, v46, v44
	v_mul_f32_e32 v46, v45, v44
	v_fma_f32 v47, -v43, v46, v45
	v_fmac_f32_e32 v46, v47, v44
	v_fma_f32 v43, -v43, v46, v45
	v_div_fmas_f32 v43, v43, v44, v46
	v_div_fixup_f32 v26, v43, v42, v26
	ds_write_b32 v2, v26 offset:36864
	s_waitcnt vmcnt(14)
	v_mul_f32_e32 v42, 0xbfb8aa3b, v27
	v_exp_f32_e32 v42, v42
	s_nop 0
	v_add_f32_e32 v42, 1.0, v42
	v_div_scale_f32 v43, s[4:5], v42, v42, v27
	v_rcp_f32_e32 v44, v43
	v_div_scale_f32 v45, vcc, v27, v42, v27
	v_fma_f32 v46, -v43, v44, 1.0
	v_fmac_f32_e32 v44, v46, v44
	v_mul_f32_e32 v46, v45, v44
	v_fma_f32 v47, -v43, v46, v45
	v_fmac_f32_e32 v46, v47, v44
	v_fma_f32 v43, -v43, v46, v45
	v_div_fmas_f32 v43, v43, v44, v46
	v_div_fixup_f32 v27, v43, v42, v27
	ds_write_b32 v2, v27 offset:38912
	s_waitcnt vmcnt(13)
	v_mul_f32_e32 v42, 0xbfb8aa3b, v28
	v_exp_f32_e32 v42, v42
	s_nop 0
	v_add_f32_e32 v42, 1.0, v42
	v_div_scale_f32 v43, s[4:5], v42, v42, v28
	v_rcp_f32_e32 v44, v43
	v_div_scale_f32 v45, vcc, v28, v42, v28
	v_fma_f32 v46, -v43, v44, 1.0
	v_fmac_f32_e32 v44, v46, v44
	v_mul_f32_e32 v46, v45, v44
	v_fma_f32 v47, -v43, v46, v45
	v_fmac_f32_e32 v46, v47, v44
	v_fma_f32 v43, -v43, v46, v45
	v_div_fmas_f32 v43, v43, v44, v46
	v_div_fixup_f32 v28, v43, v42, v28
	ds_write_b32 v2, v28 offset:40960
	s_waitcnt vmcnt(12)
	v_mul_f32_e32 v42, 0xbfb8aa3b, v29
	v_exp_f32_e32 v42, v42
	s_nop 0
	v_add_f32_e32 v42, 1.0, v42
	v_div_scale_f32 v43, s[4:5], v42, v42, v29
	v_rcp_f32_e32 v44, v43
	v_div_scale_f32 v45, vcc, v29, v42, v29
	v_fma_f32 v46, -v43, v44, 1.0
	v_fmac_f32_e32 v44, v46, v44
	v_mul_f32_e32 v46, v45, v44
	v_fma_f32 v47, -v43, v46, v45
	v_fmac_f32_e32 v46, v47, v44
	v_fma_f32 v43, -v43, v46, v45
	v_div_fmas_f32 v43, v43, v44, v46
	v_div_fixup_f32 v29, v43, v42, v29
	ds_write_b32 v2, v29 offset:43008
	s_waitcnt vmcnt(11)
	v_mul_f32_e32 v42, 0xbfb8aa3b, v30
	v_exp_f32_e32 v42, v42
	s_nop 0
	v_add_f32_e32 v42, 1.0, v42
	v_div_scale_f32 v43, s[4:5], v42, v42, v30
	v_rcp_f32_e32 v44, v43
	v_div_scale_f32 v45, vcc, v30, v42, v30
	v_fma_f32 v46, -v43, v44, 1.0
	v_fmac_f32_e32 v44, v46, v44
	v_mul_f32_e32 v46, v45, v44
	v_fma_f32 v47, -v43, v46, v45
	v_fmac_f32_e32 v46, v47, v44
	v_fma_f32 v43, -v43, v46, v45
	v_div_fmas_f32 v43, v43, v44, v46
	v_div_fixup_f32 v30, v43, v42, v30
	ds_write_b32 v2, v30 offset:45056
	s_waitcnt vmcnt(10)
	v_mul_f32_e32 v42, 0xbfb8aa3b, v31
	v_exp_f32_e32 v42, v42
	s_nop 0
	v_add_f32_e32 v42, 1.0, v42
	v_div_scale_f32 v43, s[4:5], v42, v42, v31
	v_rcp_f32_e32 v44, v43
	v_div_scale_f32 v45, vcc, v31, v42, v31
	v_fma_f32 v46, -v43, v44, 1.0
	v_fmac_f32_e32 v44, v46, v44
	v_mul_f32_e32 v46, v45, v44
	v_fma_f32 v47, -v43, v46, v45
	v_fmac_f32_e32 v46, v47, v44
	v_fma_f32 v43, -v43, v46, v45
	v_div_fmas_f32 v43, v43, v44, v46
	v_div_fixup_f32 v31, v43, v42, v31
	ds_write_b32 v2, v31 offset:47104
	s_waitcnt vmcnt(9)
	v_mul_f32_e32 v42, 0xbfb8aa3b, v32
	v_exp_f32_e32 v42, v42
	s_nop 0
	v_add_f32_e32 v42, 1.0, v42
	v_div_scale_f32 v43, s[4:5], v42, v42, v32
	v_rcp_f32_e32 v44, v43
	v_div_scale_f32 v45, vcc, v32, v42, v32
	v_fma_f32 v46, -v43, v44, 1.0
	v_fmac_f32_e32 v44, v46, v44
	v_mul_f32_e32 v46, v45, v44
	v_fma_f32 v47, -v43, v46, v45
	v_fmac_f32_e32 v46, v47, v44
	v_fma_f32 v43, -v43, v46, v45
	v_div_fmas_f32 v43, v43, v44, v46
	v_div_fixup_f32 v32, v43, v42, v32
	ds_write_b32 v2, v32 offset:49152
	s_waitcnt vmcnt(8)
	v_mul_f32_e32 v42, 0xbfb8aa3b, v33
	v_exp_f32_e32 v42, v42
	s_nop 0
	v_add_f32_e32 v42, 1.0, v42
	v_div_scale_f32 v43, s[4:5], v42, v42, v33
	v_rcp_f32_e32 v44, v43
	v_div_scale_f32 v45, vcc, v33, v42, v33
	v_fma_f32 v46, -v43, v44, 1.0
	v_fmac_f32_e32 v44, v46, v44
	v_mul_f32_e32 v46, v45, v44
	v_fma_f32 v47, -v43, v46, v45
	v_fmac_f32_e32 v46, v47, v44
	v_fma_f32 v43, -v43, v46, v45
	v_div_fmas_f32 v43, v43, v44, v46
	v_div_fixup_f32 v33, v43, v42, v33
	ds_write_b32 v2, v33 offset:51200
	s_waitcnt vmcnt(7)
	v_mul_f32_e32 v42, 0xbfb8aa3b, v34
	v_exp_f32_e32 v42, v42
	s_nop 0
	v_add_f32_e32 v42, 1.0, v42
	v_div_scale_f32 v43, s[4:5], v42, v42, v34
	v_rcp_f32_e32 v44, v43
	v_div_scale_f32 v45, vcc, v34, v42, v34
	v_fma_f32 v46, -v43, v44, 1.0
	v_fmac_f32_e32 v44, v46, v44
	v_mul_f32_e32 v46, v45, v44
	v_fma_f32 v47, -v43, v46, v45
	v_fmac_f32_e32 v46, v47, v44
	v_fma_f32 v43, -v43, v46, v45
	v_div_fmas_f32 v43, v43, v44, v46
	v_div_fixup_f32 v34, v43, v42, v34
	ds_write_b32 v2, v34 offset:53248
	s_waitcnt vmcnt(6)
	v_mul_f32_e32 v42, 0xbfb8aa3b, v35
	v_exp_f32_e32 v42, v42
	s_nop 0
	v_add_f32_e32 v42, 1.0, v42
	v_div_scale_f32 v43, s[4:5], v42, v42, v35
	v_rcp_f32_e32 v44, v43
	v_div_scale_f32 v45, vcc, v35, v42, v35
	v_fma_f32 v46, -v43, v44, 1.0
	v_fmac_f32_e32 v44, v46, v44
	v_mul_f32_e32 v46, v45, v44
	v_fma_f32 v47, -v43, v46, v45
	v_fmac_f32_e32 v46, v47, v44
	v_fma_f32 v43, -v43, v46, v45
	v_div_fmas_f32 v43, v43, v44, v46
	v_div_fixup_f32 v35, v43, v42, v35
	ds_write_b32 v2, v35 offset:55296
	s_waitcnt vmcnt(5)
	v_mul_f32_e32 v42, 0xbfb8aa3b, v36
	v_exp_f32_e32 v42, v42
	s_nop 0
	v_add_f32_e32 v42, 1.0, v42
	v_div_scale_f32 v43, s[4:5], v42, v42, v36
	v_rcp_f32_e32 v44, v43
	v_div_scale_f32 v45, vcc, v36, v42, v36
	v_fma_f32 v46, -v43, v44, 1.0
	v_fmac_f32_e32 v44, v46, v44
	v_mul_f32_e32 v46, v45, v44
	v_fma_f32 v47, -v43, v46, v45
	v_fmac_f32_e32 v46, v47, v44
	v_fma_f32 v43, -v43, v46, v45
	v_div_fmas_f32 v43, v43, v44, v46
	v_div_fixup_f32 v36, v43, v42, v36
	ds_write_b32 v2, v36 offset:57344
	s_waitcnt vmcnt(4)
	v_mul_f32_e32 v42, 0xbfb8aa3b, v37
	v_exp_f32_e32 v42, v42
	s_nop 0
	v_add_f32_e32 v42, 1.0, v42
	v_div_scale_f32 v43, s[4:5], v42, v42, v37
	v_rcp_f32_e32 v44, v43
	v_div_scale_f32 v45, vcc, v37, v42, v37
	v_fma_f32 v46, -v43, v44, 1.0
	v_fmac_f32_e32 v44, v46, v44
	v_mul_f32_e32 v46, v45, v44
	v_fma_f32 v47, -v43, v46, v45
	v_fmac_f32_e32 v46, v47, v44
	v_fma_f32 v43, -v43, v46, v45
	v_div_fmas_f32 v43, v43, v44, v46
	v_div_fixup_f32 v37, v43, v42, v37
	ds_write_b32 v2, v37 offset:59392
	s_waitcnt vmcnt(3)
	v_mul_f32_e32 v42, 0xbfb8aa3b, v38
	v_exp_f32_e32 v42, v42
	s_nop 0
	v_add_f32_e32 v42, 1.0, v42
	v_div_scale_f32 v43, s[4:5], v42, v42, v38
	v_rcp_f32_e32 v44, v43
	v_div_scale_f32 v45, vcc, v38, v42, v38
	v_fma_f32 v46, -v43, v44, 1.0
	v_fmac_f32_e32 v44, v46, v44
	v_mul_f32_e32 v46, v45, v44
	v_fma_f32 v47, -v43, v46, v45
	v_fmac_f32_e32 v46, v47, v44
	v_fma_f32 v43, -v43, v46, v45
	v_div_fmas_f32 v43, v43, v44, v46
	v_div_fixup_f32 v38, v43, v42, v38
	ds_write_b32 v2, v38 offset:61440
	s_waitcnt vmcnt(2)
	v_mul_f32_e32 v42, 0xbfb8aa3b, v39
	v_exp_f32_e32 v42, v42
	s_nop 0
	v_add_f32_e32 v42, 1.0, v42
	v_div_scale_f32 v43, s[4:5], v42, v42, v39
	v_rcp_f32_e32 v44, v43
	v_div_scale_f32 v45, vcc, v39, v42, v39
	v_fma_f32 v46, -v43, v44, 1.0
	v_fmac_f32_e32 v44, v46, v44
	v_mul_f32_e32 v46, v45, v44
	v_fma_f32 v47, -v43, v46, v45
	v_fmac_f32_e32 v46, v47, v44
	v_fma_f32 v43, -v43, v46, v45
	v_div_fmas_f32 v43, v43, v44, v46
	v_div_fixup_f32 v39, v43, v42, v39
	ds_write_b32 v2, v39 offset:63488
	s_waitcnt vmcnt(1)
	v_mul_f32_e32 v42, 0xbfb8aa3b, v40
	v_exp_f32_e32 v42, v42
	s_nop 0
	v_add_f32_e32 v42, 1.0, v42
	v_div_scale_f32 v43, s[4:5], v42, v42, v40
	v_rcp_f32_e32 v44, v43
	v_div_scale_f32 v45, vcc, v40, v42, v40
	v_fma_f32 v46, -v43, v44, 1.0
	v_fmac_f32_e32 v44, v46, v44
	v_mul_f32_e32 v46, v45, v44
	v_fma_f32 v47, -v43, v46, v45
	v_fmac_f32_e32 v46, v47, v44
	v_fma_f32 v43, -v43, v46, v45
	v_div_fmas_f32 v43, v43, v44, v46
	v_div_fixup_f32 v40, v43, v42, v40
	ds_write_b32 v6, v40
	s_waitcnt vmcnt(0)
	v_mul_f32_e32 v42, 0xbfb8aa3b, v41
	v_exp_f32_e32 v42, v42
	s_nop 0
	v_add_f32_e32 v42, 1.0, v42
	v_div_scale_f32 v43, s[4:5], v42, v42, v41
	v_rcp_f32_e32 v44, v43
	v_div_scale_f32 v45, vcc, v41, v42, v41
	v_fma_f32 v46, -v43, v44, 1.0
	v_fmac_f32_e32 v44, v46, v44
	v_mul_f32_e32 v46, v45, v44
	v_fma_f32 v47, -v43, v46, v45
	v_fmac_f32_e32 v46, v47, v44
	v_fma_f32 v43, -v43, v46, v45
	v_div_fmas_f32 v43, v43, v44, v46
	v_div_fixup_f32 v41, v43, v42, v41
	ds_write_b32 v6, v41 offset:2048
